# v54_q1
# speedup vs baseline: 1.0019x; 1.0019x over previous
; __global__ void __launch_bounds__(512) fwd(Args a_) {
;     ...
;         } else if (PHM(2) && sp == 2) { PHASE_PROLOGUE
;             if ((G & 7) == 0 && G >= 128) { if (bx < 128) compress_item(c, a, L, (bx & 7) * 16 + (bx >> 3), lds, wave, lane, tid); }
;             else for (int it = bx; it < 128; it += G) compress_item(c, a, L, it, lds, wave, lane, tid);
;             {
;                 const int xq = (G & 7) == 0 ? (bx & 7) : 0, nxq = (G & 7) == 0 ? 8 : 1;
;                 unsigned* qctr = (unsigned*)(a.ws + WS_CTL) + 8192 + 64 * (16 + 8 * L + xq);
;                 const int nsb = 2048 / nxq, nsw = 4096 / nxq;
;                 for (;;) {
;                     int li = 0; if (lane == 0) li = (int)atomicAdd(qctr, 1u);
;                     li = __builtin_amdgcn_readfirstlane(li);
;                     if (li >= nsb + nsw) break;
;                     const int it = li < nsb ? xq * nsb + li : 2048 + xq * nsw + (li - nsb);
;                     if (it < 2048) sb_item(c, 511 - (it >> 2), it & 3, lane);
;                     else { const int k = it - 2048; swa_item(c, a.in[3] + L * 8, k >> 3, k & 7, lane); }
;                 }
;             }
;         } else if (PHM(3) && sp == 3) { PHASE_PROLOGUE
;             const unsigned* kmx = (const unsigned*)(a.ws + WS_CTL) + 8192 + 64 * (8 + 2 * L);
;             const float kb0 = 8.f * 1.01f * __uint_as_float(kmx[0]), kb1 = 8.f * 1.01f * __uint_as_float(kmx[64]);
;             const int gwx = ((G & 7) == 0 ? (bx & 7) * (G >> 3) + (bx >> 3) : bx) * 8 + wave;
;             for (int k = gwx; k < 2048; k += NGW) { nsa_item8(c, 2047 - (k >> 1), 1 - (k & 1), lds, wave, lane, (k & 1) ? kb0 : kb1); nsa_item8(c, k >> 1, k & 1, lds, wave, lane, (k & 1) ? kb1 : kb0); }
;         } else if (PHM(4) && sp == 4) { PHASE_PROLOGUE
.LBB0_158:
	s_and_b64 vcc, exec, s[6:7]
	s_cbranch_vccz .LBB0_1228
	s_cmp_gt_i32 s44, 1
	s_mov_b64 s[6:7], -1
	s_cbranch_scc0 .LBB0_1173
	s_cmp_gt_i32 s44, 2
	v_writelane_b32 v244, s84, 28
	s_cbranch_scc0 .LBB0_1098
	v_readlane_b32 s101, v244, 7
	v_readlane_b32 s84, v244, 28
	s_nop 1
	s_bitcmp1_b32 s101, 0
	s_cbranch_scc0 .Lcq_p3_cont
	v_writelane_b32 v246, 1, 1
	s_lshl_b32 s100, s84, 1
	s_add_i32 s100, s100, 9
	s_branch .Lcq_entry
